# baseline (speedup 1.0000x reference)
; DI float h2lo(unsigned u) { return (float)__builtin_bit_cast(f16x2_t, u)[0]; }
; DI float h2hi(unsigned u) { return (float)__builtin_bit_cast(f16x2_t, u)[1]; }
; DI int my_tid() { int t = tid_raw(); asm volatile("" : "+v"(t)); return t; }
; DI float shfl_xor_l(float v, int mask, int lane) { return __int_as_float(__builtin_amdgcn_ds_bpermute((lane ^ mask) << 2, __float_as_int(v))); }
; DI void ln_phase(const Params& p, const u16* src, const float* g, const float* b, float* dstf, u16* dstb) {
;   const int lane = my_tid() & 63, wid = my_tid() >> 6;
;   const int stride = gridDim.x * 8;
;   int row = blockIdx.x * 8 + wid;
;   u32x2 raw[4], nxt[4];
;   f32x4 gv[4], bv[4];
; #pragma unroll
;   for (int i = 0; i < 4; ++i) { gv[i] = *(const f32x4*)(g + i * 256 + lane * 4); bv[i] = *(const f32x4*)(b + i * 256 + lane * 4); }
;   if (row < S) {
; #pragma unroll
;     for (int i = 0; i < 4; ++i) raw[i] = *(const u32x2*)(src + (size_t)row * D + i * 256 + lane * 4);
;   }
;   for (; row < S; row += stride) {
;     const int rn = row + stride;
;     if (rn < S) {
; #pragma unroll
;       for (int i = 0; i < 4; ++i) nxt[i] = *(const u32x2*)(src + (size_t)rn * D + i * 256 + lane * 4);
;     }
;     f32x4 v[4];
;     float s = 0.f;
; #pragma unroll
;     for (int i = 0; i < 4; ++i) { v[i] = (f32x4){h2lo(raw[i][0]), h2hi(raw[i][0]), h2lo(raw[i][1]), h2hi(raw[i][1])}; s += (v[i][0] + v[i][1]) + (v[i][2] + v[i][3]); }
; #pragma unroll
;     for (int o = 32; o >= 1; o >>= 1) s += shfl_xor_l(s, o, lane);
.LBB0_1109:
	s_movk_i32 s59, 0x3c0
	s_movk_i32 s58, 0x3000
	s_or_b64 exec, exec, s[8:9]
	s_waitcnt lgkmcnt(0)
	s_barrier
	s_getreg_b32 s2, hwreg(HW_REG_HW_ID, 0, 6)
	s_lshl_b32 s2, s2, 2
	s_and_b32 s2, s2, 0xfc
	s_add_i32 s2, s2, 0x20040
	v_mov_b32_e32 v0, s2
	ds_read_b32 v0, v0
	s_lshl_b32 s92, s69, 10
	s_waitcnt lgkmcnt(0)
	v_readfirstlane_b32 s2, v0
	s_nop 1
	v_lshl_or_b32 v34, s2, 6, v214
	s_getreg_b32 s2, hwreg(HW_REG_HW_ID, 0, 6)
	s_lshl_b32 s2, s2, 2
	s_and_b32 s2, s2, 0xfc
	s_add_i32 s2, s2, 0x20040
	v_mov_b32_e32 v0, s2
	ds_read_b32 v0, v0
	s_waitcnt lgkmcnt(0)
	v_readfirstlane_b32 s2, v0
	s_nop 1
	v_lshl_or_b32 v0, s2, 6, v214
	v_readlane_b32 s2, v255, 12
	v_ashrrev_i32_e32 v36, 6, v0
	s_nop 0
	v_add_u32_e32 v32, s2, v36
	s_movk_i32 s2, 0x4000
	v_cmp_gt_i32_e32 vcc, s2, v32
	s_and_saveexec_b64 s[8:9], vcc
	s_cbranch_execz .LBB0_1114
	s_lshl_b64 s[2:3], s[92:93], 2
	v_readlane_b32 s36, v252, 18
	v_readlane_b32 s37, v252, 19
	s_add_u32 s22, s36, s2
	v_readlane_b32 s38, v252, 20
	s_addc_u32 s23, s37, s3
	v_lshlrev_b32_e32 v35, 2, v34
	v_readlane_b32 s39, v252, 21
	s_add_u32 s2, s38, s2
	v_and_b32_e32 v37, 0xfc, v35
	s_addc_u32 s3, s39, s3
	v_lshlrev_b32_e32 v28, 2, v37
	global_load_dwordx4 v[0:3], v28, s[22:23]
	global_load_dwordx4 v[4:7], v28, s[22:23] offset:1024
	global_load_dwordx4 v[8:11], v28, s[2:3]
	global_load_dwordx4 v[12:15], v28, s[2:3] offset:1024
	global_load_dwordx4 v[16:19], v28, s[22:23] offset:2048
	global_load_dwordx4 v[20:23], v28, s[22:23] offset:3072
	global_load_dwordx4 v[24:27], v28, s[2:3] offset:2048
	s_nop 0
	global_load_dwordx4 v[28:31], v28, s[2:3] offset:3072
	v_ashrrev_i32_e32 v33, 31, v32
	v_readlane_b32 s2, v254, 14
	v_lshlrev_b64 v[38:39], 11, v[32:33]
	v_readlane_b32 s3, v254, 15
	v_lshlrev_b32_e32 v64, 1, v37
	v_bfrev_b32_e32 v37, 0.5
	v_lshl_add_u64 v[40:41], s[2:3], 0, v[38:39]
	v_lshl_add_u64 v[40:41], v[40:41], 0, v[64:65]
	global_load_dwordx2 v[52:53], v[40:41], off
	global_load_dwordx2 v[50:51], v[40:41], off offset:512
	global_load_dwordx2 v[48:49], v[40:41], off offset:1024
	global_load_dwordx2 v[46:47], v[40:41], off offset:1536
	s_movk_i32 s2, 0x80
	v_bitop3_b32 v33, v35, s2, v37 bitop3:0x6c
	v_readlane_b32 s2, v255, 13
	v_bitop3_b32 v54, v35, 64, v37 bitop3:0x6c
	v_bitop3_b32 v55, v35, 32, v37 bitop3:0x6c
	v_add_u32_e32 v36, s2, v36
	v_bitop3_b32 v56, v35, 16, v37 bitop3:0x6c
	v_bitop3_b32 v57, v35, 8, v37 bitop3:0x6c
	v_bitop3_b32 v58, v35, 4, v37 bitop3:0x6c
	v_and_b32_e32 v34, 63, v34
	v_ashrrev_i32_e32 v37, 31, v36
	v_lshlrev_b32_e32 v64, 3, v34
	v_lshl_add_u64 v[34:35], s[90:91], 0, v[38:39]
	v_lshlrev_b64 v[36:37], 11, v[36:37]
	v_mov_b32_e32 v38, 0
	v_lshl_add_u64 v[36:37], s[90:91], 0, v[36:37]
	s_mov_b64 s[22:23], 0
	v_mov_b32_e32 v39, v38
	v_mov_b32_e32 v40, v38
	v_mov_b32_e32 v41, v38
	v_mov_b32_e32 v42, v38
	v_mov_b32_e32 v43, v38
	v_mov_b32_e32 v44, v38
	v_mov_b32_e32 v45, v38
	v_readlane_b32 s40, v252, 22
	v_readlane_b32 s41, v252, 23
	v_readlane_b32 s42, v252, 24
	v_readlane_b32 s43, v252, 25
	v_readlane_b32 s44, v252, 26
	v_readlane_b32 s45, v252, 27
	v_readlane_b32 s46, v252, 28
	v_readlane_b32 s47, v252, 29
	v_readlane_b32 s48, v252, 30
	v_readlane_b32 s49, v252, 31
	v_readlane_b32 s50, v252, 32
	v_readlane_b32 s51, v252, 33
	s_waitcnt vmcnt(0)
	s_branch .LBB0_1112
.LBB0_1111:
	s_or_b64 exec, exec, s[28:29]
	v_cvt_f32_f16_sdwa v60, v52 dst_sel:DWORD dst_unused:UNUSED_PAD src0_sel:WORD_1
	v_cvt_f32_f16_e32 v62, v52
	v_cvt_f32_f16_sdwa v61, v53 dst_sel:DWORD dst_unused:UNUSED_PAD src0_sel:WORD_1
	v_cvt_f32_f16_e32 v63, v53
	v_cvt_f32_f16_e32 v66, v50
	v_cvt_f32_f16_e32 v67, v51
	v_cvt_f32_f16_sdwa v68, v46 dst_sel:DWORD dst_unused:UNUSED_PAD src0_sel:WORD_1
	v_pk_add_f32 v[60:61], v[62:63], v[60:61]
	v_cvt_f32_f16_sdwa v62, v50 dst_sel:DWORD dst_unused:UNUSED_PAD src0_sel:WORD_1
	v_cvt_f32_f16_sdwa v63, v51 dst_sel:DWORD dst_unused:UNUSED_PAD src0_sel:WORD_1
	v_add_f32_e32 v59, v60, v61
	v_add_f32_e32 v61, 0, v59
	v_cvt_f32_f16_sdwa v59, v48 dst_sel:DWORD dst_unused:UNUSED_PAD src0_sel:WORD_1
	v_pk_add_f32 v[62:63], v[66:67], v[62:63]
	v_cvt_f32_f16_e32 v60, v48
	v_pk_add_f32 v[62:63], v[62:63], v[62:63] op_sel_hi:[0,1]
	v_cvt_f32_f16_sdwa v62, v49 dst_sel:DWORD dst_unused:UNUSED_PAD src0_sel:WORD_1
	v_cvt_f32_f16_e32 v66, v49
	v_add_f32_e32 v67, v60, v59
	v_cvt_f32_f16_sdwa v60, v47 dst_sel:DWORD dst_unused:UNUSED_PAD src0_sel:WORD_1
	s_and_b64 s[2:3], exec, s[38:39]
	v_add_f32_e32 v69, v66, v62
	v_cvt_f32_f16_e32 v66, v46
	v_cvt_f32_f16_e32 v62, v47
	s_or_b64 s[22:23], s[2:3], s[22:23]
	v_pk_add_f32 v[66:67], v[66:67], v[68:69]
	v_pk_add_f32 v[60:61], v[62:63], v[60:61]
	s_nop 0
	v_pk_add_f32 v[60:61], v[66:67], v[60:61]
	s_nop 0
	v_add_f32_e32 v59, v60, v61
	s_nop 1
	v_add_f32_dpp v59, v59, v59 quad_perm:[1,0,3,2] row_mask:0xf bank_mask:0xf
	s_nop 1
	v_add_f32_dpp v59, v59, v59 quad_perm:[2,3,0,1] row_mask:0xf bank_mask:0xf
	s_nop 1
	v_add_f32_dpp v59, v59, v59 row_half_mirror row_mask:0xf bank_mask:0xf
	s_nop 1
	v_add_f32_dpp v59, v59, v59 row_mirror row_mask:0xf bank_mask:0xf
	v_mov_b32_e32 v60, v59
	s_nop 1
	v_permlane16_swap_b32 v60, v59
	v_add_f32_e32 v59, v59, v60
	v_mov_b32_e32 v60, v59
	s_nop 1
	v_permlane32_swap_b32 v60, v59
	v_add_f32_e32 v59, v59, v60
	v_fma_mix_f32 v61, v59, s65, v52 op_sel:[0,0,1] op_sel_hi:[0,0,1]
	v_fma_mix_f32 v60, v59, s65, v52 op_sel_hi:[0,0,1]
; DI unsigned pk_bf16(float lo, float hi) { f32x2_t v = {lo, hi}; return __builtin_bit_cast(unsigned, __builtin_convertvector(v, bf16x2_t)); }
; DI float shfl_xor_l(float v, int mask, int lane) { return __int_as_float(__builtin_amdgcn_ds_bpermute((lane ^ mask) << 2, __float_as_int(v))); }
; DI void ln_phase(const Params& p, const u16* src, const float* g, const float* b, float* dstf, u16* dstb) {
;     ...
;     for (int o = 32; o >= 1; o >>= 1) s += shfl_xor_l(s, o, lane);
;     const float mu = s * (1.0f / 1024.0f);
;     float q = 0.f;
; #pragma unroll
;     for (int i = 0; i < 4; ++i) { v[i] = v[i] - mu; q += (v[i][0] * v[i][0] + v[i][1] * v[i][1]) + (v[i][2] * v[i][2] + v[i][3] * v[i][3]); }
; #pragma unroll
;     for (int o = 32; o >= 1; o >>= 1) q += shfl_xor_l(q, o, lane);
;     const float rstd = 1.0f / sqrtf(q * (1.0f / 1024.0f) + 1e-5f);
; #pragma unroll
;     for (int i = 0; i < 4; ++i) {
;       const int col = i * 256 + lane * 4;
;       const f32x4 o = v[i] * rstd * gv[i] + bv[i];
;       if (dstf) *(f32x4*)(dstf + (size_t)row * D + col) = o;
;       if (dstb) { u32x2 ob; ob[0] = pk_bf16(o[0], o[1]); ob[1] = pk_bf16(o[2], o[3]); *(u32x2*)(dstb + (size_t)row * D + col) = ob; }
;     }
; #pragma unroll
;     for (int i = 0; i < 4; ++i) raw[i] = nxt[i];
	v_fma_mix_f32 v63, v59, s65, v53 op_sel:[0,0,1] op_sel_hi:[0,0,1]
	v_fma_mix_f32 v62, v59, s65, v53 op_sel_hi:[0,0,1]
	v_pk_mul_f32 v[52:53], v[62:63], v[62:63]
	v_pk_mul_f32 v[66:67], v[60:61], v[60:61]
	v_fma_mix_f32 v77, v59, s65, v47 op_sel:[0,0,1] op_sel_hi:[0,0,1]
	v_pk_mov_b32 v[68:69], v[66:67], v[52:53] op_sel:[1,0]
	v_mov_b32_e32 v67, v53
	v_pk_add_f32 v[52:53], v[68:69], v[66:67]
	v_fma_mix_f32 v67, v59, s65, v50 op_sel:[0,0,1] op_sel_hi:[0,0,1]
	v_fma_mix_f32 v66, v59, s65, v50 op_sel_hi:[0,0,1]
	v_fma_mix_f32 v69, v59, s65, v51 op_sel:[0,0,1] op_sel_hi:[0,0,1]
	v_fma_mix_f32 v68, v59, s65, v51 op_sel_hi:[0,0,1]
	v_pk_mul_f32 v[50:51], v[68:69], v[68:69]
	v_pk_mul_f32 v[70:71], v[66:67], v[66:67]
	v_pk_add_f32 v[52:53], v[52:53], v[52:53] op_sel_hi:[0,1]
	v_pk_mov_b32 v[72:73], v[70:71], v[50:51] op_sel:[1,0]
	v_mov_b32_e32 v71, v51
	v_pk_add_f32 v[50:51], v[72:73], v[70:71]
	v_fma_mix_f32 v70, v59, s65, v48 op_sel_hi:[0,0,1]
	v_fma_mix_f32 v71, v59, s65, v48 op_sel:[0,0,1] op_sel_hi:[0,0,1]
	v_mul_f32_e32 v48, v70, v70
	v_fma_mix_f32 v73, v59, s65, v49 op_sel:[0,0,1] op_sel_hi:[0,0,1]
	v_fma_mix_f32 v72, v59, s65, v49 op_sel_hi:[0,0,1]
	v_pk_fma_f32 v[48:49], v[70:71], v[70:71], v[48:49] op_sel_hi:[1,1,0]
	v_pk_add_f32 v[50:51], v[50:51], v[50:51] op_sel_hi:[0,1]
	v_mul_f32_e32 v48, v72, v72
	v_pk_fma_f32 v[74:75], v[72:73], v[72:73], v[48:49] op_sel_hi:[1,1,0]
	v_fma_mix_f32 v76, v59, s65, v47 op_sel_hi:[0,0,1]
	v_fma_mix_f32 v47, v59, s65, v46 op_sel:[0,0,1] op_sel_hi:[0,0,1]
	v_fma_mix_f32 v46, v59, s65, v46 op_sel_hi:[0,0,1]
	v_mul_f32_e32 v48, v46, v46
	v_mul_f32_e32 v74, v47, v47
	v_mul_f32_e32 v52, v76, v76
	v_mul_f32_e32 v50, v77, v77
	v_pk_add_f32 v[48:49], v[48:49], v[74:75]
	v_pk_add_f32 v[50:51], v[52:53], v[50:51]
	s_nop 0
	v_pk_add_f32 v[48:49], v[48:49], v[50:51]
	s_nop 0
	v_add_f32_e32 v48, v48, v49
	s_nop 1
	v_add_f32_dpp v48, v48, v48 quad_perm:[1,0,3,2] row_mask:0xf bank_mask:0xf
	s_nop 1
	v_add_f32_dpp v48, v48, v48 quad_perm:[2,3,0,1] row_mask:0xf bank_mask:0xf
	s_nop 1
	v_add_f32_dpp v48, v48, v48 row_half_mirror row_mask:0xf bank_mask:0xf
	s_nop 1
	v_add_f32_dpp v48, v48, v48 row_mirror row_mask:0xf bank_mask:0xf
	v_mov_b32_e32 v49, v48
	s_nop 1
	v_permlane16_swap_b32 v49, v48
	v_add_f32_e32 v48, v48, v49
	v_mov_b32_e32 v49, v48
	s_nop 1
	v_permlane32_swap_b32 v49, v48
	v_add_f32_e32 v48, v48, v49
	v_mov_b32_e32 v49, 0x3727c5ac
	v_fmamk_f32 v48, v48, 0x3a800000, v49
	v_cmp_gt_f32_e32 vcc, s66, v48
	v_mul_f32_e32 v49, 0x4f800000, v48
	s_nop 0
	v_cndmask_b32_e32 v48, v48, v49, vcc
	v_sqrt_f32_e32 v49, v48
	s_nop 0
	v_add_u32_e32 v50, -1, v49
	v_fma_f32 v51, -v50, v49, v48
	v_cmp_ge_f32_e64 s[38:39], 0, v51
	v_add_u32_e32 v51, 1, v49
	s_nop 0
	v_cndmask_b32_e64 v50, v49, v50, s[38:39]
	v_fma_f32 v49, -v51, v49, v48
	v_cmp_lt_f32_e64 s[38:39], 0, v49
	s_nop 1
	v_cndmask_b32_e64 v49, v50, v51, s[38:39]
	v_mul_f32_e32 v50, 0x37800000, v49
	v_cndmask_b32_e32 v49, v49, v50, vcc
	v_mov_b32_e32 v50, 0x260
	v_cmp_class_f32_e32 vcc, v48, v50
	s_nop 1
	v_cndmask_b32_e32 v48, v49, v48, vcc
	v_div_scale_f32 v49, s[2:3], v48, v48, 1.0
	v_rcp_f32_e32 v50, v49
	s_mov_b32 s2, 0xaa80000
	v_fma_f32 v51, -v49, v50, 1.0
	v_fmac_f32_e32 v50, v51, v50
	v_div_scale_f32 v51, vcc, 1.0, v48, 1.0
	v_mul_f32_e32 v52, v51, v50
	v_fma_f32 v53, -v49, v52, v51
	v_fmac_f32_e32 v52, v53, v50
	v_fma_f32 v49, -v49, v52, v51
	v_div_fmas_f32 v49, v49, v50, v52
	v_div_fixup_f32 v48, v49, v48, 1.0
	v_pk_mul_f32 v[50:51], v[60:61], v[48:49] op_sel_hi:[1,0]
	v_pk_mul_f32 v[52:53], v[62:63], v[48:49] op_sel_hi:[1,0]
	v_pk_fma_f32 v[50:51], v[0:1], v[50:51], v[8:9]
	v_pk_fma_f32 v[52:53], v[2:3], v[52:53], v[10:11]
	v_cvt_pk_bf16_f32 v50, v50, v51
	v_cvt_pk_bf16_f32 v51, v52, v53
	v_lshl_add_u64 v[52:53], v[34:35], 0, v[64:65]
	v_add_co_u32_e32 v52, vcc, s2, v52
	v_pk_mul_f32 v[60:61], v[68:69], v[48:49] op_sel_hi:[1,0]
	s_nop 0
	v_addc_co_u32_e32 v53, vcc, 0, v53, vcc
	global_store_dwordx2 v[52:53], v[50:51], off
	v_pk_mul_f32 v[50:51], v[66:67], v[48:49] op_sel_hi:[1,0]
	v_pk_fma_f32 v[60:61], v[6:7], v[60:61], v[14:15]
	v_pk_fma_f32 v[50:51], v[4:5], v[50:51], v[12:13]
	v_pk_mul_f32 v[46:47], v[46:47], v[48:49] op_sel_hi:[1,0]
	v_cvt_pk_bf16_f32 v50, v50, v51
	v_cvt_pk_bf16_f32 v51, v60, v61
	global_store_dwordx2 v[52:53], v[50:51], off offset:512
	v_pk_mul_f32 v[50:51], v[70:71], v[48:49] op_sel_hi:[1,0]
	v_pk_mul_f32 v[60:61], v[72:73], v[48:49] op_sel_hi:[1,0]
	v_pk_mul_f32 v[48:49], v[76:77], v[48:49] op_sel_hi:[1,0]
	v_pk_fma_f32 v[60:61], v[18:19], v[60:61], v[26:27]
	v_pk_fma_f32 v[50:51], v[16:17], v[50:51], v[24:25]
	v_pk_fma_f32 v[48:49], v[22:23], v[48:49], v[30:31]
	v_pk_fma_f32 v[46:47], v[20:21], v[46:47], v[28:29]
	v_readlane_b32 s2, v255, 14
	v_cvt_pk_bf16_f32 v50, v50, v51
	v_cvt_pk_bf16_f32 v51, v60, v61
	v_cvt_pk_bf16_f32 v46, v46, v47
	v_cvt_pk_bf16_f32 v47, v48, v49
	v_readlane_b32 s3, v255, 15
	global_store_dwordx2 v[52:53], v[50:51], off offset:1024
	global_store_dwordx2 v[52:53], v[46:47], off offset:1536
	v_lshl_add_u64 v[34:35], v[34:35], 0, s[2:3]
	v_lshl_add_u64 v[36:37], v[36:37], 0, s[2:3]
	s_waitcnt vmcnt(4)
	v_mov_b32_e32 v52, v38
	v_mov_b32_e32 v53, v39
	v_mov_b32_e32 v50, v40
	v_mov_b32_e32 v51, v41
	v_mov_b32_e32 v48, v42
	v_mov_b32_e32 v49, v43
	v_mov_b32_e32 v46, v44
	v_mov_b32_e32 v47, v45
	s_andn2_b64 exec, exec, s[22:23]
	s_cbranch_execz .LBB0_1114

; DI float h2lo(unsigned u) { return (float)__builtin_bit_cast(f16x2_t, u)[0]; }
; DI float h2hi(unsigned u) { return (float)__builtin_bit_cast(f16x2_t, u)[1]; }
; DI int my_tid() { int t = tid_raw(); asm volatile("" : "+v"(t)); return t; }
; DI void ln_phase(const Params& p, const u16* src, const float* g, const float* b, float* dstf, u16* dstb) {
;   const int lane = my_tid() & 63, wid = my_tid() >> 6;
;   const int stride = gridDim.x * 8;
;   int row = blockIdx.x * 8 + wid;
;   u32x2 raw[4], nxt[4];
;   f32x4 gv[4], bv[4];
; #pragma unroll
;   for (int i = 0; i < 4; ++i) { gv[i] = *(const f32x4*)(g + i * 256 + lane * 4); bv[i] = *(const f32x4*)(b + i * 256 + lane * 4); }
;   if (row < S) {
; #pragma unroll
;     for (int i = 0; i < 4; ++i) raw[i] = *(const u32x2*)(src + (size_t)row * D + i * 256 + lane * 4);
;   }
;   for (; row < S; row += stride) {
;     const int rn = row + stride;
;     if (rn < S) {
; #pragma unroll
;       for (int i = 0; i < 4; ++i) nxt[i] = *(const u32x2*)(src + (size_t)rn * D + i * 256 + lane * 4);
;     }
;     f32x4 v[4];
;     float s = 0.f;
; #pragma unroll
;     for (int i = 0; i < 4; ++i) { v[i] = (f32x4){h2lo(raw[i][0]), h2hi(raw[i][0]), h2lo(raw[i][1]), h2hi(raw[i][1])}; s += (v[i][0] + v[i][1]) + (v[i][2] + v[i][3]); }
.LBB0_1322:
	s_or_b64 exec, exec, s[8:9]
	s_waitcnt lgkmcnt(0)
	s_barrier
	s_getreg_b32 s2, hwreg(HW_REG_HW_ID, 0, 6)
	s_lshl_b32 s2, s2, 2
	s_and_b32 s2, s2, 0xfc
	s_add_i32 s2, s2, 0x20040
	v_mov_b32_e32 v0, s2
	ds_read_b32 v0, v0
	s_waitcnt lgkmcnt(0)
	v_readfirstlane_b32 s2, v0
	s_nop 1
	v_lshl_or_b32 v38, s2, 6, v214
	s_getreg_b32 s2, hwreg(HW_REG_HW_ID, 0, 6)
	s_lshl_b32 s2, s2, 2
	s_and_b32 s2, s2, 0xfc
	s_add_i32 s2, s2, 0x20040
	v_mov_b32_e32 v0, s2
	ds_read_b32 v0, v0
	s_waitcnt lgkmcnt(0)
	v_readfirstlane_b32 s2, v0
	s_nop 1
	v_lshl_or_b32 v0, s2, 6, v214
	v_readlane_b32 s2, v255, 12
	v_ashrrev_i32_e32 v39, 6, v0
	s_nop 0
	v_add_u32_e32 v36, s2, v39
	s_movk_i32 s2, 0x4000
	v_cmp_gt_i32_e32 vcc, s2, v36
	s_and_saveexec_b64 s[8:9], vcc
	s_cbranch_execz .LBB0_1343
	s_lshl_b64 s[2:3], s[92:93], 2
	s_add_u32 s22, s84, s2
	s_addc_u32 s23, s85, s3
	v_lshlrev_b32_e32 v42, 2, v38
	s_add_u32 s2, s86, s2
	v_and_b32_e32 v34, 0xfc, v42
	s_addc_u32 s3, s87, s3
	v_lshlrev_b32_e32 v28, 2, v34
	global_load_dwordx4 v[0:3], v28, s[22:23]
	global_load_dwordx4 v[4:7], v28, s[22:23] offset:1024
	global_load_dwordx4 v[8:11], v28, s[2:3]
	global_load_dwordx4 v[12:15], v28, s[2:3] offset:1024
	global_load_dwordx4 v[16:19], v28, s[22:23] offset:2048
	global_load_dwordx4 v[20:23], v28, s[22:23] offset:3072
	global_load_dwordx4 v[24:27], v28, s[2:3] offset:2048
	s_nop 0
	global_load_dwordx4 v[28:31], v28, s[2:3] offset:3072
	v_ashrrev_i32_e32 v37, 31, v36
	v_readlane_b32 s2, v254, 20
	v_lshlrev_b64 v[40:41], 11, v[36:37]
	v_readlane_b32 s3, v254, 21
	v_lshlrev_b32_e32 v64, 1, v34
	s_movk_i32 s7, 0x80
	v_lshl_add_u64 v[32:33], s[2:3], 0, v[40:41]
	v_lshl_add_u64 v[32:33], v[32:33], 0, v[64:65]
	global_load_dwordx2 v[54:55], v[32:33], off
	global_load_dwordx2 v[52:53], v[32:33], off offset:512
	global_load_dwordx2 v[34:35], v[32:33], off offset:1024
	s_nop 0
	global_load_dwordx2 v[32:33], v[32:33], off offset:1536
	s_and_b64 s[2:3], s[46:47], exec
	v_bfrev_b32_e32 v43, 0.5
	v_readlane_b32 s2, v254, 22
	v_bitop3_b32 v70, v42, s7, v43 bitop3:0x6c
	v_readlane_b32 s7, v255, 13
	v_readlane_b32 s3, v254, 23
	v_readlane_b32 s36, v255, 29
	v_bitop3_b32 v71, v42, 64, v43 bitop3:0x6c
	v_bitop3_b32 v72, v42, 32, v43 bitop3:0x6c
	v_bitop3_b32 v73, v42, 16, v43 bitop3:0x6c
	v_bitop3_b32 v74, v42, 8, v43 bitop3:0x6c
	v_bitop3_b32 v75, v42, 4, v43 bitop3:0x6c
	v_and_b32_e32 v44, 63, v38
	v_add_u32_e32 v38, s7, v39
	v_lshlrev_b64 v[42:43], 12, v[36:37]
	s_cselect_b32 s3, s3, 0
	s_cselect_b32 s2, s2, 0
	v_readlane_b32 s37, v255, 30
	v_ashrrev_i32_e32 v39, 31, v38
	v_lshl_or_b32 v42, v44, 4, v42
	s_cmp_lg_u64 s[36:37], 0
	v_lshlrev_b32_e32 v64, 3, v44
	v_lshlrev_b64 v[38:39], 11, v[38:39]
	v_lshl_add_u64 v[40:41], s[2:3], 0, v[40:41]
	v_lshl_add_u64 v[42:43], s[36:37], 0, v[42:43]
	s_mov_b64 s[2:3], 0x800
	v_mov_b32_e32 v44, 0
	s_mov_b64 s[22:23], 0
	s_cselect_b64 s[28:29], -1, 0
	v_lshl_add_u64 v[38:39], s[90:91], 0, v[38:39]
	v_lshl_add_u64 v[42:43], v[42:43], 0, s[2:3]
	v_mov_b32_e32 v45, v44
	v_mov_b32_e32 v46, v44
	v_mov_b32_e32 v47, v44
	v_mov_b32_e32 v48, v44
	v_mov_b32_e32 v49, v44
	v_mov_b32_e32 v50, v44
	v_mov_b32_e32 v51, v44
	s_waitcnt vmcnt(0)
	s_branch .LBB0_1325
.LBB0_1324:
	s_waitcnt vmcnt(4)
	s_and_b64 s[2:3], exec, s[36:37]
	s_or_b64 s[22:23], s[2:3], s[22:23]
	v_readlane_b32 s2, v255, 14
	v_readlane_b32 s3, v255, 15
	v_readlane_b32 s40, v255, 40
	v_mov_b32_e32 v54, v44
	v_lshl_add_u64 v[38:39], v[38:39], 0, s[2:3]
	v_lshl_add_u64 v[40:41], v[40:41], 0, s[2:3]
	v_readlane_b32 s2, v255, 18
	v_readlane_b32 s3, v255, 19
	v_mov_b32_e32 v55, v45
	v_mov_b32_e32 v52, v46
	v_lshl_add_u64 v[42:43], v[42:43], 0, s[2:3]
	v_mov_b32_e32 v53, v47
	v_mov_b32_e32 v34, v48
	v_mov_b32_e32 v35, v49
	v_mov_b32_e32 v32, v50
	v_mov_b32_e32 v33, v51
	v_readlane_b32 s41, v255, 41
	s_andn2_b64 exec, exec, s[22:23]
	s_cbranch_execz .LBB0_1343

; DI float h2lo(unsigned u) { return (float)__builtin_bit_cast(f16x2_t, u)[0]; }
; DI float h2hi(unsigned u) { return (float)__builtin_bit_cast(f16x2_t, u)[1]; }
; DI float shfl_xor_l(float v, int mask, int lane) { return __int_as_float(__builtin_amdgcn_ds_bpermute((lane ^ mask) << 2, __float_as_int(v))); }
; DI void ln_phase(const Params& p, const u16* src, const float* g, const float* b, float* dstf, u16* dstb) {
;     ...
;     for (int i = 0; i < 4; ++i) { v[i] = (f32x4){h2lo(raw[i][0]), h2hi(raw[i][0]), h2lo(raw[i][1]), h2hi(raw[i][1])}; s += (v[i][0] + v[i][1]) + (v[i][2] + v[i][3]); }
; #pragma unroll
;     for (int o = 32; o >= 1; o >>= 1) s += shfl_xor_l(s, o, lane);
;     const float mu = s * (1.0f / 1024.0f);
;     float q = 0.f;
; #pragma unroll
;     for (int i = 0; i < 4; ++i) { v[i] = v[i] - mu; q += (v[i][0] * v[i][0] + v[i][1] * v[i][1]) + (v[i][2] * v[i][2] + v[i][3] * v[i][3]); }
; #pragma unroll
;     for (int o = 32; o >= 1; o >>= 1) q += shfl_xor_l(q, o, lane);
;     const float rstd = 1.0f / sqrtf(q * (1.0f / 1024.0f) + 1e-5f);
; #pragma unroll
;     for (int i = 0; i < 4; ++i) {
;       const int col = i * 256 + lane * 4;
;       const f32x4 o = v[i] * rstd * gv[i] + bv[i];
;       if (dstf) *(f32x4*)(dstf + (size_t)row * D + col) = o;
.LBB0_1327:
	s_or_b64 exec, exec, s[38:39]
	v_cvt_f32_f16_sdwa v56, v54 dst_sel:DWORD dst_unused:UNUSED_PAD src0_sel:WORD_1
	v_cvt_f32_f16_e32 v58, v54
	v_cvt_f32_f16_sdwa v57, v55 dst_sel:DWORD dst_unused:UNUSED_PAD src0_sel:WORD_1
	v_cvt_f32_f16_e32 v59, v55
	v_cvt_f32_f16_sdwa v60, v52 dst_sel:DWORD dst_unused:UNUSED_PAD src0_sel:WORD_1
	v_cvt_f32_f16_e32 v62, v52
	v_cvt_f32_f16_sdwa v61, v53 dst_sel:DWORD dst_unused:UNUSED_PAD src0_sel:WORD_1
	v_cvt_f32_f16_e32 v63, v53
	v_pk_add_f32 v[56:57], v[58:59], v[56:57]
	v_cvt_f32_f16_sdwa v66, v35 dst_sel:DWORD dst_unused:UNUSED_PAD src0_sel:WORD_1
	v_add_f32_e32 v37, v56, v57
	v_pk_add_f32 v[58:59], v[62:63], v[60:61]
	v_add_f32_e32 v57, 0, v37
	v_pk_add_f32 v[58:59], v[58:59], v[58:59] op_sel_hi:[0,1]
	v_cvt_f32_f16_sdwa v37, v34 dst_sel:DWORD dst_unused:UNUSED_PAD src0_sel:WORD_1
	v_cvt_f32_f16_e32 v61, v34
	v_cvt_f32_f16_e32 v67, v35
	v_cvt_f32_f16_sdwa v60, v32 dst_sel:DWORD dst_unused:UNUSED_PAD src0_sel:WORD_1
	v_cvt_f32_f16_e32 v62, v32
	v_cvt_f32_f16_sdwa v56, v33 dst_sel:DWORD dst_unused:UNUSED_PAD src0_sel:WORD_1
	v_cvt_f32_f16_e32 v58, v33
	v_add_f32_e32 v63, v61, v37
	v_add_f32_e32 v61, v67, v66
	v_pk_add_f32 v[60:61], v[62:63], v[60:61]
	v_pk_add_f32 v[56:57], v[58:59], v[56:57]
	s_nop 0
	v_pk_add_f32 v[56:57], v[60:61], v[56:57]
	s_nop 0
	v_add_f32_e32 v37, v56, v57
	s_nop 1
	v_add_f32_dpp v37, v37, v37 quad_perm:[1,0,3,2] row_mask:0xf bank_mask:0xf
	s_nop 1
	v_add_f32_dpp v37, v37, v37 quad_perm:[2,3,0,1] row_mask:0xf bank_mask:0xf
	s_nop 1
	v_add_f32_dpp v37, v37, v37 row_half_mirror row_mask:0xf bank_mask:0xf
	s_nop 1
	v_add_f32_dpp v37, v37, v37 row_mirror row_mask:0xf bank_mask:0xf
	v_mov_b32_e32 v56, v37
	s_nop 1
	v_permlane16_swap_b32 v56, v37
	v_add_f32_e32 v37, v37, v56
	v_mov_b32_e32 v56, v37
	s_nop 1
	v_permlane32_swap_b32 v56, v37
	v_add_f32_e32 v37, v37, v56
	v_fma_mix_f32 v67, v37, s65, v54 op_sel:[0,0,1] op_sel_hi:[0,0,1]
	v_fma_mix_f32 v66, v37, s65, v54 op_sel_hi:[0,0,1]
	v_fma_mix_f32 v77, v37, s65, v55 op_sel:[0,0,1] op_sel_hi:[0,0,1]
	v_fma_mix_f32 v76, v37, s65, v55 op_sel_hi:[0,0,1]
	v_fma_mix_f32 v61, v37, s65, v53 op_sel:[0,0,1] op_sel_hi:[0,0,1]
	v_fma_mix_f32 v60, v37, s65, v53 op_sel_hi:[0,0,1]
	v_fma_mix_f32 v63, v37, s65, v52 op_sel:[0,0,1] op_sel_hi:[0,0,1]
	v_fma_mix_f32 v62, v37, s65, v52 op_sel_hi:[0,0,1]
	v_pk_mul_f32 v[52:53], v[76:77], v[76:77]
	v_pk_mul_f32 v[54:55], v[66:67], v[66:67]
	v_pk_mul_f32 v[56:57], v[60:61], v[60:61]
	v_pk_mov_b32 v[58:59], v[54:55], v[52:53] op_sel:[1,0]
	v_mov_b32_e32 v55, v53
	v_pk_add_f32 v[52:53], v[58:59], v[54:55]
	v_fma_mix_f32 v58, v37, s65, v34 op_sel_hi:[0,0,1]
	v_pk_add_f32 v[68:69], v[52:53], v[52:53] op_sel_hi:[0,1]
	v_pk_mul_f32 v[52:53], v[62:63], v[62:63]
	v_fma_mix_f32 v59, v37, s65, v34 op_sel:[0,0,1] op_sel_hi:[0,0,1]
	v_mul_f32_e32 v34, v58, v58
	v_pk_mov_b32 v[54:55], v[52:53], v[56:57] op_sel:[1,0]
	v_mov_b32_e32 v53, v57
	v_fma_mix_f32 v57, v37, s65, v35 op_sel:[0,0,1] op_sel_hi:[0,0,1]
	v_fma_mix_f32 v56, v37, s65, v35 op_sel_hi:[0,0,1]
	v_pk_fma_f32 v[34:35], v[58:59], v[58:59], v[34:35] op_sel_hi:[1,1,0]
	v_pk_add_f32 v[52:53], v[54:55], v[52:53]
	v_mul_f32_e32 v34, v56, v56
	v_pk_add_f32 v[78:79], v[52:53], v[52:53] op_sel_hi:[0,1]
	v_pk_fma_f32 v[80:81], v[56:57], v[56:57], v[34:35] op_sel_hi:[1,1,0]
	v_fma_mix_f32 v53, v37, s65, v33 op_sel:[0,0,1] op_sel_hi:[0,0,1]
	v_fma_mix_f32 v52, v37, s65, v33 op_sel_hi:[0,0,1]
	v_fma_mix_f32 v55, v37, s65, v32 op_sel:[0,0,1] op_sel_hi:[0,0,1]
	v_fma_mix_f32 v54, v37, s65, v32 op_sel_hi:[0,0,1]
	v_mul_f32_e32 v34, v54, v54
	v_mul_f32_e32 v80, v55, v55
	v_mul_f32_e32 v68, v52, v52
	v_mul_f32_e32 v78, v53, v53
	v_pk_add_f32 v[32:33], v[34:35], v[80:81]
	v_pk_add_f32 v[34:35], v[68:69], v[78:79]
	s_nop 0
	v_pk_add_f32 v[32:33], v[32:33], v[34:35]
	s_nop 0
	v_add_f32_e32 v32, v32, v33
	s_nop 1
	v_add_f32_dpp v32, v32, v32 quad_perm:[1,0,3,2] row_mask:0xf bank_mask:0xf
	s_nop 1
	v_add_f32_dpp v32, v32, v32 quad_perm:[2,3,0,1] row_mask:0xf bank_mask:0xf
	s_nop 1
	v_add_f32_dpp v32, v32, v32 row_half_mirror row_mask:0xf bank_mask:0xf
	s_nop 1
	v_add_f32_dpp v32, v32, v32 row_mirror row_mask:0xf bank_mask:0xf
	v_mov_b32_e32 v33, v32
	s_nop 1
	v_permlane16_swap_b32 v33, v32
	v_add_f32_e32 v32, v32, v33
	v_mov_b32_e32 v33, v32
	s_nop 1
	v_permlane32_swap_b32 v33, v32
	v_add_f32_e32 v32, v32, v33
	v_mov_b32_e32 v33, 0x3727c5ac
	v_fmamk_f32 v32, v32, 0x3a800000, v33
	v_mul_f32_e32 v33, 0x4f800000, v32
	v_cmp_gt_f32_e32 vcc, s66, v32
	s_nop 1
	v_cndmask_b32_e32 v32, v32, v33, vcc
	v_sqrt_f32_e32 v33, v32
	s_nop 0
	v_add_u32_e32 v34, -1, v33
	v_add_u32_e32 v35, 1, v33
	v_fma_f32 v37, -v34, v33, v32
	v_fma_f32 v68, -v35, v33, v32
	v_cmp_ge_f32_e64 s[38:39], 0, v37
	s_nop 1
	v_cndmask_b32_e64 v33, v33, v34, s[38:39]
	v_cmp_lt_f32_e64 s[38:39], 0, v68
	s_nop 1
	v_cndmask_b32_e64 v33, v33, v35, s[38:39]
	v_mul_f32_e32 v34, 0x37800000, v33
	v_cndmask_b32_e32 v33, v33, v34, vcc
	v_mov_b32_e32 v34, 0x260
	v_cmp_class_f32_e32 vcc, v32, v34
	s_nop 1
	v_cndmask_b32_e32 v32, v33, v32, vcc
	v_div_scale_f32 v33, s[2:3], v32, v32, 1.0
	v_rcp_f32_e32 v34, v33
	v_div_scale_f32 v35, vcc, 1.0, v32, 1.0
	v_fma_f32 v37, -v33, v34, 1.0
	v_fmac_f32_e32 v34, v37, v34
	v_mul_f32_e32 v37, v35, v34
	v_fma_f32 v68, -v33, v37, v35
	v_fmac_f32_e32 v37, v68, v34
	v_fma_f32 v33, -v33, v37, v35
	v_div_fmas_f32 v33, v33, v34, v37
	v_div_fixup_f32 v68, v33, v32, 1.0
	v_pk_mul_f32 v[32:33], v[66:67], v[68:69] op_sel_hi:[1,0]
	v_pk_mul_f32 v[34:35], v[76:77], v[68:69] op_sel_hi:[1,0]
	v_cndmask_b32_e64 v37, 0, 1, s[28:29]
	v_pk_fma_f32 v[34:35], v[2:3], v[34:35], v[10:11]
	v_cmp_ne_u32_e64 s[38:39], 1, v37
	s_andn2_b64 vcc, exec, s[28:29]
	v_pk_fma_f32 v[32:33], v[0:1], v[32:33], v[8:9]
	s_cbranch_vccnz .LBB0_1329
	global_store_dwordx4 v[42:43], v[32:35], off offset:-2048
